# cross-half permlane max exchange moved into the rare rescale path (per-half threshold test is equivalent)
# speedup vs baseline: 1.0467x; 1.0006x over previous
.Latt_swa_nomask:
	v_max3_f32 v198, v64, v65, v66
	v_max3_f32 v199, v67, v68, v69
	v_max3_f32 v198, v198, v70, v71
	v_max3_f32 v199, v199, v72, v73
	v_max3_f32 v198, v198, v74, v75
	v_max3_f32 v199, v199, v76, v77
	v_max3_f32 v198, v198, v78, v79
	v_max3_f32 v200, v32, v33, v34
	v_max3_f32 v201, v35, v36, v37
	v_max3_f32 v200, v200, v38, v39
	v_max3_f32 v201, v201, v40, v41
	v_max3_f32 v200, v200, v42, v43
	v_max3_f32 v201, v201, v44, v45
	v_max3_f32 v200, v200, v46, v47
	v_max3_f32 v198, v198, v199, v200
	v_max_f32_e32 v198, v198, v201
	v_cmp_lt_f32_e32 vcc, s58, v198
	s_cbranch_vccz .Latt_swa_norescale
.Latt_swa_rare:
	v_mov_b32_e32 v199, v198
	s_nop 1
	v_permlane32_swap_b32_e32 v198, v199
	v_max_f32_e32 v202, v198, v199
	v_max_f32_e32 v203, 0, v202
	v_max_f32_e32 v204, 0, v203
	v_add_f32_e32 v131, v131, v203
	v_exp_f32_e64 v206, -v204
	v_sub_f32_e32 v154, v154, v203
	v_mov_b32_e32 v155, v154
	v_mov_b32_e32 v156, v154
	v_mov_b32_e32 v157, v154
	v_mov_b32_e32 v158, v154
	v_mov_b32_e32 v159, v154
	v_mov_b32_e32 v160, v154
	v_mov_b32_e32 v161, v154
	v_mov_b32_e32 v162, v154
	v_mov_b32_e32 v163, v154
	v_mov_b32_e32 v164, v154
	v_mov_b32_e32 v165, v154
	v_mov_b32_e32 v166, v154
	v_mov_b32_e32 v167, v154
	v_mov_b32_e32 v168, v154
	v_mov_b32_e32 v169, v154
	v_sub_f32_e32 v64, v64, v203
	v_sub_f32_e32 v65, v65, v203
	v_sub_f32_e32 v66, v66, v203
	v_sub_f32_e32 v67, v67, v203
	v_sub_f32_e32 v68, v68, v203
	v_sub_f32_e32 v69, v69, v203
	v_sub_f32_e32 v70, v70, v203
	v_sub_f32_e32 v71, v71, v203
	v_sub_f32_e32 v72, v72, v203
	v_sub_f32_e32 v73, v73, v203
	v_sub_f32_e32 v74, v74, v203
	v_sub_f32_e32 v75, v75, v203
	v_sub_f32_e32 v76, v76, v203
	v_sub_f32_e32 v77, v77, v203
	v_sub_f32_e32 v78, v78, v203
	v_sub_f32_e32 v79, v79, v203
	v_sub_f32_e32 v32, v32, v203
	v_sub_f32_e32 v33, v33, v203
	v_sub_f32_e32 v34, v34, v203
	v_sub_f32_e32 v35, v35, v203
	v_sub_f32_e32 v36, v36, v203
	v_sub_f32_e32 v37, v37, v203
	v_sub_f32_e32 v38, v38, v203
	v_sub_f32_e32 v39, v39, v203
	v_sub_f32_e32 v40, v40, v203
	v_sub_f32_e32 v41, v41, v203
	v_sub_f32_e32 v42, v42, v203
	v_sub_f32_e32 v43, v43, v203
	v_sub_f32_e32 v44, v44, v203
	v_sub_f32_e32 v45, v45, v203
	v_sub_f32_e32 v46, v46, v203
	v_sub_f32_e32 v47, v47, v203
	v_mul_f32_e32 v121, v121, v206
	v_pk_mul_f32 v[0:1], v[0:1], v[206:207] op_sel_hi:[1,0]
	v_pk_mul_f32 v[2:3], v[2:3], v[206:207] op_sel_hi:[1,0]
	v_pk_mul_f32 v[4:5], v[4:5], v[206:207] op_sel_hi:[1,0]
	v_pk_mul_f32 v[6:7], v[6:7], v[206:207] op_sel_hi:[1,0]
	v_pk_mul_f32 v[8:9], v[8:9], v[206:207] op_sel_hi:[1,0]
	v_pk_mul_f32 v[10:11], v[10:11], v[206:207] op_sel_hi:[1,0]
	v_pk_mul_f32 v[12:13], v[12:13], v[206:207] op_sel_hi:[1,0]
	v_pk_mul_f32 v[14:15], v[14:15], v[206:207] op_sel_hi:[1,0]
	v_pk_mul_f32 v[16:17], v[16:17], v[206:207] op_sel_hi:[1,0]
	v_pk_mul_f32 v[18:19], v[18:19], v[206:207] op_sel_hi:[1,0]
	v_pk_mul_f32 v[20:21], v[20:21], v[206:207] op_sel_hi:[1,0]
	v_pk_mul_f32 v[22:23], v[22:23], v[206:207] op_sel_hi:[1,0]
	v_pk_mul_f32 v[24:25], v[24:25], v[206:207] op_sel_hi:[1,0]
	v_pk_mul_f32 v[26:27], v[26:27], v[206:207] op_sel_hi:[1,0]
	v_pk_mul_f32 v[28:29], v[28:29], v[206:207] op_sel_hi:[1,0]
	v_pk_mul_f32 v[30:31], v[30:31], v[206:207] op_sel_hi:[1,0]

.LBB0_116:
	s_mul_i32 s30, s53, 0x2400
	v_add_u32_e32 v242, s30, v173
	ds_read_b128 v[112:115], v242 offset:0
	ds_read_b128 v[116:119], v242 offset:4608
	ds_read_b128 v[120:123], v242 offset:32
	ds_read_b128 v[124:127], v242 offset:4640
	ds_read_b128 v[202:205], v242 offset:64
	ds_read_b128 v[206:209], v242 offset:4672
	ds_read_b128 v[210:213], v242 offset:96
	ds_read_b128 v[214:217], v242 offset:4704
	s_mul_i32 s30, s53, 0x4800
	v_add_u32_e32 v243, s30, v174
	s_waitcnt lgkmcnt(7)
	v_mfma_f32_32x32x16_bf16 v[64:79], v[112:115], v[130:133], v[96:111]
	s_waitcnt lgkmcnt(6)
	v_mfma_f32_32x32x16_bf16 v[80:95], v[116:119], v[130:133], v[96:111]
	s_waitcnt lgkmcnt(5)
	v_mfma_f32_32x32x16_bf16 v[64:79], v[120:123], v[134:137], v[64:79]
	s_waitcnt lgkmcnt(4)
	v_mfma_f32_32x32x16_bf16 v[80:95], v[124:127], v[134:137], v[80:95]
	s_waitcnt lgkmcnt(3)
	v_mfma_f32_32x32x16_bf16 v[64:79], v[202:205], v[138:141], v[64:79]
	s_waitcnt lgkmcnt(2)
	v_mfma_f32_32x32x16_bf16 v[80:95], v[206:209], v[138:141], v[80:95]
	s_waitcnt lgkmcnt(1)
	v_mfma_f32_32x32x16_bf16 v[64:79], v[210:213], v[142:145], v[64:79]
	s_waitcnt lgkmcnt(0)
	v_mfma_f32_32x32x16_bf16 v[80:95], v[214:217], v[142:145], v[80:95]
	ds_read_b128 v[112:115], v243 offset:27648
	ds_read_b128 v[116:119], v243 offset:32256
	ds_read_b128 v[120:123], v243 offset:36864
	ds_read_b128 v[124:127], v243 offset:41472
	ds_read_b128 v[202:205], v243 offset:27680
	ds_read_b128 v[206:209], v243 offset:32288
	ds_read_b128 v[210:213], v243 offset:36896
	ds_read_b128 v[214:217], v243 offset:41504
	s_cmp_eq_u32 s52, 0
	s_cselect_b32 s31, 0xff7fffff, 0
	s_nop 0
	v_max3_f32 v226, v64, v65, v66
	v_max3_f32 v227, v67, v68, v69
	v_max3_f32 v226, v226, v70, v71
	v_max3_f32 v227, v227, v72, v73
	v_max3_f32 v226, v226, v74, v75
	v_max3_f32 v227, v227, v76, v77
	v_max3_f32 v226, v226, v78, v79
	v_max3_f32 v228, v80, v81, v82
	v_max3_f32 v229, v83, v84, v85
	v_max3_f32 v228, v228, v86, v87
	v_max3_f32 v229, v229, v88, v89
	v_max3_f32 v228, v228, v90, v91
	v_max3_f32 v229, v229, v92, v93
	v_max3_f32 v228, v228, v94, v95
	v_max3_f32 v226, v226, v227, v228
	v_max_f32_e32 v226, v226, v229
	v_cmp_lt_f32_e32 vcc, s58, v226
	s_cmp_eq_u32 s52, 0
	s_cbranch_scc1 .Latt_diff_rare
	s_cbranch_vccz .Latt_diff_norescale
.Latt_diff_rare:
	v_mov_b32_e32 v227, v226
	s_nop 1
	v_permlane32_swap_b32_e32 v226, v227
	v_max_f32_e32 v237, v226, v227
	v_max_f32_e32 v238, s31, v237
	v_max_f32_e32 v239, 0, v238
	v_add_f32_e32 v159, v159, v238
	v_exp_f32_e64 v240, -v239
	v_sub_f32_e32 v96, v96, v238
	v_mov_b32_e32 v97, v96
	v_mov_b32_e32 v98, v96
	v_mov_b32_e32 v99, v96
	v_mov_b32_e32 v100, v96
	v_mov_b32_e32 v101, v96
	v_mov_b32_e32 v102, v96
	v_mov_b32_e32 v103, v96
	v_mov_b32_e32 v104, v96
	v_mov_b32_e32 v105, v96
	v_mov_b32_e32 v106, v96
	v_mov_b32_e32 v107, v96
	v_mov_b32_e32 v108, v96
	v_mov_b32_e32 v109, v96
	v_mov_b32_e32 v110, v96
	v_mov_b32_e32 v111, v96
	v_sub_f32_e32 v64, v64, v238
	v_sub_f32_e32 v65, v65, v238
	v_sub_f32_e32 v66, v66, v238
	v_sub_f32_e32 v67, v67, v238
	v_sub_f32_e32 v68, v68, v238
	v_sub_f32_e32 v69, v69, v238
	v_sub_f32_e32 v70, v70, v238
	v_sub_f32_e32 v71, v71, v238
	v_sub_f32_e32 v72, v72, v238
	v_sub_f32_e32 v73, v73, v238
	v_sub_f32_e32 v74, v74, v238
	v_sub_f32_e32 v75, v75, v238
	v_sub_f32_e32 v76, v76, v238
	v_sub_f32_e32 v77, v77, v238
	v_sub_f32_e32 v78, v78, v238
	v_sub_f32_e32 v79, v79, v238
	v_sub_f32_e32 v80, v80, v238
	v_sub_f32_e32 v81, v81, v238
	v_sub_f32_e32 v82, v82, v238
	v_sub_f32_e32 v83, v83, v238
	v_sub_f32_e32 v84, v84, v238
	v_sub_f32_e32 v85, v85, v238
	v_sub_f32_e32 v86, v86, v238
	v_sub_f32_e32 v87, v87, v238
	v_sub_f32_e32 v88, v88, v238
	v_sub_f32_e32 v89, v89, v238
	v_sub_f32_e32 v90, v90, v238
	v_sub_f32_e32 v91, v91, v238
	v_sub_f32_e32 v92, v92, v238
	v_sub_f32_e32 v93, v93, v238
	v_sub_f32_e32 v94, v94, v238
	v_sub_f32_e32 v95, v95, v238
	v_mul_f32_e32 v157, v157, v240
	v_pk_mul_f32 v[0:1], v[0:1], v[240:241] op_sel_hi:[1,0]
	v_pk_mul_f32 v[2:3], v[2:3], v[240:241] op_sel_hi:[1,0]
	v_pk_mul_f32 v[4:5], v[4:5], v[240:241] op_sel_hi:[1,0]
	v_pk_mul_f32 v[6:7], v[6:7], v[240:241] op_sel_hi:[1,0]
	v_pk_mul_f32 v[8:9], v[8:9], v[240:241] op_sel_hi:[1,0]
	v_pk_mul_f32 v[10:11], v[10:11], v[240:241] op_sel_hi:[1,0]
	v_pk_mul_f32 v[12:13], v[12:13], v[240:241] op_sel_hi:[1,0]
	v_pk_mul_f32 v[14:15], v[14:15], v[240:241] op_sel_hi:[1,0]
	v_pk_mul_f32 v[48:49], v[48:49], v[240:241] op_sel_hi:[1,0]
	v_pk_mul_f32 v[50:51], v[50:51], v[240:241] op_sel_hi:[1,0]
	v_pk_mul_f32 v[52:53], v[52:53], v[240:241] op_sel_hi:[1,0]
	v_pk_mul_f32 v[54:55], v[54:55], v[240:241] op_sel_hi:[1,0]
	v_pk_mul_f32 v[56:57], v[56:57], v[240:241] op_sel_hi:[1,0]
	v_pk_mul_f32 v[58:59], v[58:59], v[240:241] op_sel_hi:[1,0]
	v_pk_mul_f32 v[60:61], v[60:61], v[240:241] op_sel_hi:[1,0]
	v_pk_mul_f32 v[62:63], v[62:63], v[240:241] op_sel_hi:[1,0]
	v_pk_mul_f32 v[32:33], v[32:33], v[240:241] op_sel_hi:[1,0]
	v_pk_mul_f32 v[34:35], v[34:35], v[240:241] op_sel_hi:[1,0]
	v_pk_mul_f32 v[36:37], v[36:37], v[240:241] op_sel_hi:[1,0]
	v_pk_mul_f32 v[38:39], v[38:39], v[240:241] op_sel_hi:[1,0]
	v_pk_mul_f32 v[40:41], v[40:41], v[240:241] op_sel_hi:[1,0]
	v_pk_mul_f32 v[42:43], v[42:43], v[240:241] op_sel_hi:[1,0]
	v_pk_mul_f32 v[44:45], v[44:45], v[240:241] op_sel_hi:[1,0]
	v_pk_mul_f32 v[46:47], v[46:47], v[240:241] op_sel_hi:[1,0]
	v_pk_mul_f32 v[16:17], v[16:17], v[240:241] op_sel_hi:[1,0]
	v_pk_mul_f32 v[18:19], v[18:19], v[240:241] op_sel_hi:[1,0]
	v_pk_mul_f32 v[20:21], v[20:21], v[240:241] op_sel_hi:[1,0]
	v_pk_mul_f32 v[22:23], v[22:23], v[240:241] op_sel_hi:[1,0]
	v_pk_mul_f32 v[24:25], v[24:25], v[240:241] op_sel_hi:[1,0]
	v_pk_mul_f32 v[26:27], v[26:27], v[240:241] op_sel_hi:[1,0]
	v_pk_mul_f32 v[28:29], v[28:29], v[240:241] op_sel_hi:[1,0]
	v_pk_mul_f32 v[30:31], v[30:31], v[240:241] op_sel_hi:[1,0]

.LBB0_191:
	s_mul_i32 s30, s56, 0x6400
	v_add_u32_e32 v209, s30, v246
	ds_read_b128 v[112:115], v209 offset:0
	ds_read_b128 v[116:119], v209 offset:12800
	ds_read_b128 v[120:123], v209 offset:32
	ds_read_b128 v[124:127], v209 offset:12832
	ds_read_b128 v[250:253], v209 offset:64
	s_mul_i32 s30, s56, 0x4800
	v_add_u32_e32 v219, s30, v247
	s_waitcnt lgkmcnt(4)
	v_mfma_f32_32x32x16_bf16 v[64:79], v[112:115], v[130:133], v[96:111]
	ds_read_b128 v[112:115], v209 offset:12864
	s_waitcnt lgkmcnt(4)
	v_mfma_f32_32x32x16_bf16 v[80:95], v[116:119], v[130:133], v[96:111]
	ds_read_b128 v[116:119], v209 offset:96
	s_waitcnt lgkmcnt(4)
	v_mfma_f32_32x32x16_bf16 v[64:79], v[120:123], v[134:137], v[64:79]
	ds_read_b128 v[120:123], v209 offset:12896
	s_waitcnt lgkmcnt(4)
	v_mfma_f32_32x32x16_bf16 v[80:95], v[124:127], v[134:137], v[80:95]
	ds_read_b128 v[124:127], v209 offset:128
	s_waitcnt lgkmcnt(4)
	v_mfma_f32_32x32x16_bf16 v[64:79], v[250:253], v[138:141], v[64:79]
	ds_read_b128 v[250:253], v209 offset:12928
	s_waitcnt lgkmcnt(4)
	v_mfma_f32_32x32x16_bf16 v[80:95], v[112:115], v[138:141], v[80:95]
	ds_read_b128 v[112:115], v209 offset:160
	s_waitcnt lgkmcnt(4)
	v_mfma_f32_32x32x16_bf16 v[64:79], v[116:119], v[142:145], v[64:79]
	ds_read_b128 v[116:119], v209 offset:12960
	s_waitcnt lgkmcnt(4)
	v_mfma_f32_32x32x16_bf16 v[80:95], v[120:123], v[142:145], v[80:95]
	ds_read_b128 v[120:123], v209 offset:192
	s_waitcnt lgkmcnt(4)
	v_mfma_f32_32x32x16_bf16 v[64:79], v[124:127], v[146:149], v[64:79]
	ds_read_b128 v[124:127], v209 offset:12992
	s_waitcnt lgkmcnt(4)
	v_mfma_f32_32x32x16_bf16 v[80:95], v[250:253], v[146:149], v[80:95]
	ds_read_b128 v[250:253], v209 offset:224
	s_waitcnt lgkmcnt(4)
	v_mfma_f32_32x32x16_bf16 v[64:79], v[112:115], v[150:153], v[64:79]
	ds_read_b128 v[112:115], v209 offset:13024
	s_waitcnt lgkmcnt(4)
	v_mfma_f32_32x32x16_bf16 v[80:95], v[116:119], v[150:153], v[80:95]
	ds_read_b128 v[116:119], v209 offset:256
	s_waitcnt lgkmcnt(4)
	v_mfma_f32_32x32x16_bf16 v[64:79], v[120:123], v[154:157], v[64:79]
	ds_read_b128 v[120:123], v209 offset:13056
	s_waitcnt lgkmcnt(4)
	v_mfma_f32_32x32x16_bf16 v[80:95], v[124:127], v[154:157], v[80:95]
	ds_read_b128 v[124:127], v209 offset:288
	s_waitcnt lgkmcnt(4)
	v_mfma_f32_32x32x16_bf16 v[64:79], v[250:253], v[158:161], v[64:79]
	ds_read_b128 v[250:253], v209 offset:13088
	s_waitcnt lgkmcnt(4)
	v_mfma_f32_32x32x16_bf16 v[80:95], v[112:115], v[158:161], v[80:95]
	ds_read_b128 v[112:115], v209 offset:320
	s_waitcnt lgkmcnt(4)
	v_mfma_f32_32x32x16_bf16 v[64:79], v[116:119], v[162:165], v[64:79]
	ds_read_b128 v[116:119], v209 offset:13120
	s_waitcnt lgkmcnt(4)
	v_mfma_f32_32x32x16_bf16 v[80:95], v[120:123], v[162:165], v[80:95]
	ds_read_b128 v[120:123], v209 offset:352
	s_waitcnt lgkmcnt(4)
	v_mfma_f32_32x32x16_bf16 v[64:79], v[124:127], v[166:169], v[64:79]
	ds_read_b128 v[124:127], v209 offset:13152
	s_waitcnt lgkmcnt(4)
	v_mfma_f32_32x32x16_bf16 v[80:95], v[250:253], v[166:169], v[80:95]
	s_waitcnt lgkmcnt(3)
	v_mfma_f32_32x32x16_bf16 v[64:79], v[112:115], v[170:173], v[64:79]
	s_waitcnt lgkmcnt(2)
	v_mfma_f32_32x32x16_bf16 v[80:95], v[116:119], v[170:173], v[80:95]
	s_waitcnt lgkmcnt(1)
	v_mfma_f32_32x32x16_bf16 v[64:79], v[120:123], v[174:177], v[64:79]
	s_waitcnt lgkmcnt(0)
	v_mfma_f32_32x32x16_bf16 v[80:95], v[124:127], v[174:177], v[80:95]
	ds_read_b128 v[112:115], v219 offset:0
	ds_read_b128 v[116:119], v219 offset:4608
	ds_read_b128 v[120:123], v219 offset:9216
	s_cmp_eq_u32 s55, 0
	s_cselect_b32 s31, 0xff7fffff, 0
	s_nop 5
	v_max3_f32 v209, v64, v65, v66
	v_max3_f32 v211, v67, v68, v69
	v_max3_f32 v209, v209, v70, v71
	v_max3_f32 v211, v211, v72, v73
	v_max3_f32 v209, v209, v74, v75
	v_max3_f32 v211, v211, v76, v77
	v_max3_f32 v209, v209, v78, v79
	v_max3_f32 v213, v80, v81, v82
	v_max3_f32 v215, v83, v84, v85
	v_max3_f32 v213, v213, v86, v87
	v_max3_f32 v215, v215, v88, v89
	v_max3_f32 v213, v213, v90, v91
	v_max3_f32 v215, v215, v92, v93
	v_max3_f32 v213, v213, v94, v95
	v_max3_f32 v209, v209, v211, v213
	v_max_f32_e32 v209, v209, v215
	v_cmp_lt_f32_e32 vcc, s58, v209
	s_cmp_eq_u32 s55, 0
	s_cbranch_scc1 .Latt_mla_rare
	s_cbranch_vccz .Latt_mla_norescale
.Latt_mla_rare:
	v_mov_b32_e32 v211, v209
	s_nop 1
	v_permlane32_swap_b32_e32 v209, v211
	v_max_f32_e32 v217, v209, v211
	v_max_f32_e32 v211, s31, v217
	v_max_f32_e32 v213, 0, v211
	v_add_f32_e32 v207, v207, v211
	v_exp_f32_e64 v250, -v213
	v_sub_f32_e32 v96, v96, v211
	v_mov_b32_e32 v97, v96
	v_mov_b32_e32 v98, v96
	v_mov_b32_e32 v99, v96
	v_mov_b32_e32 v100, v96
	v_mov_b32_e32 v101, v96
	v_mov_b32_e32 v102, v96
	v_mov_b32_e32 v103, v96
	v_mov_b32_e32 v104, v96
	v_mov_b32_e32 v105, v96
	v_mov_b32_e32 v106, v96
	v_mov_b32_e32 v107, v96
	v_mov_b32_e32 v108, v96
	v_mov_b32_e32 v109, v96
	v_mov_b32_e32 v110, v96
	v_mov_b32_e32 v111, v96
	v_sub_f32_e32 v64, v64, v211
	v_sub_f32_e32 v65, v65, v211
	v_sub_f32_e32 v66, v66, v211
	v_sub_f32_e32 v67, v67, v211
	v_sub_f32_e32 v68, v68, v211
	v_sub_f32_e32 v69, v69, v211
	v_sub_f32_e32 v70, v70, v211
	v_sub_f32_e32 v71, v71, v211
	v_sub_f32_e32 v72, v72, v211
	v_sub_f32_e32 v73, v73, v211
	v_sub_f32_e32 v74, v74, v211
	v_sub_f32_e32 v75, v75, v211
	v_sub_f32_e32 v76, v76, v211
	v_sub_f32_e32 v77, v77, v211
	v_sub_f32_e32 v78, v78, v211
	v_sub_f32_e32 v79, v79, v211
	v_sub_f32_e32 v80, v80, v211
	v_sub_f32_e32 v81, v81, v211
	v_sub_f32_e32 v82, v82, v211
	v_sub_f32_e32 v83, v83, v211
	v_sub_f32_e32 v84, v84, v211
	v_sub_f32_e32 v85, v85, v211
	v_sub_f32_e32 v86, v86, v211
	v_sub_f32_e32 v87, v87, v211
	v_sub_f32_e32 v88, v88, v211
	v_sub_f32_e32 v89, v89, v211
	v_sub_f32_e32 v90, v90, v211
	v_sub_f32_e32 v91, v91, v211
	v_sub_f32_e32 v92, v92, v211
	v_sub_f32_e32 v93, v93, v211
	v_sub_f32_e32 v94, v94, v211
	v_sub_f32_e32 v95, v95, v211
	v_mul_f32_e32 v205, v205, v250
	v_pk_mul_f32 v[48:49], v[48:49], v[250:251] op_sel_hi:[1,0]
	v_pk_mul_f32 v[50:51], v[50:51], v[250:251] op_sel_hi:[1,0]
	v_pk_mul_f32 v[52:53], v[52:53], v[250:251] op_sel_hi:[1,0]
	v_pk_mul_f32 v[54:55], v[54:55], v[250:251] op_sel_hi:[1,0]
	v_pk_mul_f32 v[56:57], v[56:57], v[250:251] op_sel_hi:[1,0]
	v_pk_mul_f32 v[58:59], v[58:59], v[250:251] op_sel_hi:[1,0]
	v_pk_mul_f32 v[60:61], v[60:61], v[250:251] op_sel_hi:[1,0]
	v_pk_mul_f32 v[62:63], v[62:63], v[250:251] op_sel_hi:[1,0]
	v_pk_mul_f32 v[32:33], v[32:33], v[250:251] op_sel_hi:[1,0]
	v_pk_mul_f32 v[34:35], v[34:35], v[250:251] op_sel_hi:[1,0]
	v_pk_mul_f32 v[36:37], v[36:37], v[250:251] op_sel_hi:[1,0]
	v_pk_mul_f32 v[38:39], v[38:39], v[250:251] op_sel_hi:[1,0]
	v_pk_mul_f32 v[40:41], v[40:41], v[250:251] op_sel_hi:[1,0]
	v_pk_mul_f32 v[42:43], v[42:43], v[250:251] op_sel_hi:[1,0]
	v_pk_mul_f32 v[44:45], v[44:45], v[250:251] op_sel_hi:[1,0]
	v_pk_mul_f32 v[46:47], v[46:47], v[250:251] op_sel_hi:[1,0]
	v_pk_mul_f32 v[16:17], v[16:17], v[250:251] op_sel_hi:[1,0]
	v_pk_mul_f32 v[18:19], v[18:19], v[250:251] op_sel_hi:[1,0]
	v_pk_mul_f32 v[20:21], v[20:21], v[250:251] op_sel_hi:[1,0]
	v_pk_mul_f32 v[22:23], v[22:23], v[250:251] op_sel_hi:[1,0]
	v_pk_mul_f32 v[24:25], v[24:25], v[250:251] op_sel_hi:[1,0]
	v_pk_mul_f32 v[26:27], v[26:27], v[250:251] op_sel_hi:[1,0]
	v_pk_mul_f32 v[28:29], v[28:29], v[250:251] op_sel_hi:[1,0]
	v_pk_mul_f32 v[30:31], v[30:31], v[250:251] op_sel_hi:[1,0]
	v_pk_mul_f32 v[0:1], v[0:1], v[250:251] op_sel_hi:[1,0]
	v_pk_mul_f32 v[2:3], v[2:3], v[250:251] op_sel_hi:[1,0]
	v_pk_mul_f32 v[4:5], v[4:5], v[250:251] op_sel_hi:[1,0]
	v_pk_mul_f32 v[6:7], v[6:7], v[250:251] op_sel_hi:[1,0]
	v_pk_mul_f32 v[8:9], v[8:9], v[250:251] op_sel_hi:[1,0]
	v_pk_mul_f32 v[10:11], v[10:11], v[250:251] op_sel_hi:[1,0]
	v_pk_mul_f32 v[12:13], v[12:13], v[250:251] op_sel_hi:[1,0]
	v_pk_mul_f32 v[14:15], v[14:15], v[250:251] op_sel_hi:[1,0]
